# combo17 + GEMM phase prologues issue the second batch of stage loads before waiting for the first batch (both batches' latencies overlap at the start of each GEMM phase)
# baseline (speedup 1.0000x reference)
; #define PG8_STAGE(bufoff, gbase, voff) do { _Pragma("unroll") for (int _i = 0; _i < 2; ++_i) \
;         __builtin_amdgcn_global_load_lds((const unsigned*)((const char*)(gbase) + (voff)[_i]), (LAS unsigned*)(lds + (bufoff) + ldsw + _i * 8192), 16, 0, 0); } while (0)
; #define PG8_WAIT_V(n) asm volatile("s_waitcnt vmcnt(" #n ")" ::: "memory")
; #define PG8_BAR __builtin_amdgcn_s_barrier()
; template <class Epi>
; __device__ __forceinline__ void gemm_phase(LAS unsigned char* lds, const Gemm g, const StaticOrder& S, const Epi& E, const int tid) {
;     ...
;     for (int i = 0; i < 2; ++i) { int R, C; stage_rc(tid * 16 + i * 8192, R, C); const int Rb = Epi::PERM ? ((R & ~31) + perm32(R & 31)) : R;
;         voffA[i] = (unsigned)(R * g.lda + C) * 2u; voffB[i] = (unsigned)(Rb * g.ldb + C) * 2u; }
;     const size_t kstep = (size_t)(BK * 2);
;     const size_t hsA = (size_t)HALF * g.lda * 2, hsB = (size_t)HALF * g.ldb * 2;
;     const size_t tsA = 2 * hsA, tsB = 2 * hsB;
;     const unsigned ldsw = (unsigned)wid * 1024u;
;     const int aoff = lds_byte(wr * 64 + fr, fq * 8), boff = lds_byte(wc * 32 + fr, fq * 8);
;     ...
;     const char* cA = PG8_APTR(cur); const char* cB = PG8_BPTR(cur);
;     PG8_STAGE(PG8_SB(0, 0), cB, voffB); PG8_STAGE(PG8_SB(0, 1), cB + hsB, voffB); PG8_STAGE(PG8_SA(0, 0), cA, voffA); PG8_STAGE(PG8_SA(0, 1), cA + hsA, voffA);
;     if (wr == 1) PG8_BAR;
;     PG8_WAIT_V(2); PG8_BAR;
;     PG8_STAGE(PG8_SB(1, 0), cB + kstep, voffB); PG8_STAGE(PG8_SA(1, 0), cA + kstep, voffA); PG8_STAGE(PG8_SB(1, 1), cB + hsB + kstep, voffB);
;     PG8_WAIT_V(6); PG8_BAR;
.LBB0_155:
	v_mov_b32_e32 v133, v169
	v_lshl_add_u64 v[6:7], s[0:1], 0, v[168:169]
	v_readlane_b32 s34, v254, 19
	v_lshrrev_b32_e32 v14, 1, v214
	v_and_b32_e32 v15, 15, v214
	s_lshl_b32 s11, s11, 5
	v_mov_b32_e32 v129, v169
	v_lshl_add_u64 v[8:9], s[0:1], 0, v[132:133]
	v_readlane_b32 s35, v254, 20
	v_and_b32_e32 v14, 24, v14
	v_lshlrev_b32_e32 v16, 6, v15
	v_lshlrev_b32_e32 v17, 2, v214
	s_and_b32 s14, s11, 0x60
	s_add_i32 m0, s42, 0x18000
	v_lshl_add_u64 v[6:7], v[6:7], 0, s[28:29]
	v_mov_b32_e32 v131, v169
	v_lshl_add_u64 v[10:11], s[34:35], 0, v[128:129]
	v_lshl_or_b32 v16, v14, 1, v16
	v_and_b32_e32 v17, 32, v17
	v_lshl_or_b32 v142, s12, 6, v15
	s_lshl_b32 s12, s12, 13
	s_lshl_b32 s11, s14, 7
	global_load_lds_dwordx4 v[6:7], off
	v_lshl_add_u64 v[6:7], v[8:9], 0, s[28:29]
	s_add_i32 m0, s42, 0x1a000
	s_add_i32 s46, s42, 0x8000
	s_add_i32 s47, s42, 0xa000
	v_lshl_add_u64 v[12:13], s[34:35], 0, v[130:131]
	v_bitop3_b32 v15, v16, s12, v17 bitop3:0xde
	global_load_lds_dwordx4 v[6:7], off
	v_lshl_add_u64 v[6:7], v[10:11], 0, s[28:29]
	s_mov_b32 m0, s46
	s_add_u32 s12, s0, 0x80080
	global_load_lds_dwordx4 v[6:7], off
	v_lshl_add_u64 v[6:7], v[12:13], 0, s[28:29]
	s_mov_b32 m0, s47
	s_addc_u32 s13, s1, 0
	global_load_lds_dwordx4 v[6:7], off
	s_add_i32 m0, s42, 0x1c000
	v_lshl_add_u64 v[6:7], s[12:13], 0, v[168:169]
	global_load_lds_dwordx4 v[6:7], off
	v_lshl_add_u64 v[6:7], s[12:13], 0, v[132:133]
	s_add_i32 m0, s42, 0x1e000
	s_cmpk_lt_u32 s10, 0x100
	global_load_lds_dwordx4 v[6:7], off
	s_waitcnt vmcnt(8)
	s_barrier
	v_lshlrev_b32_e32 v6, 15, v0
	v_and_b32_e32 v6, 0xffff0000, v6
	v_lshl_add_u32 v1, v1, 12, v6
	v_and_b32_e32 v0, 1, v0
	v_lshl_or_b32 v0, v0, 6, v1
	v_lshl_add_u32 v134, v2, 1, v0
	v_lshlrev_b32_e32 v0, 15, v3
	v_and_b32_e32 v0, 0xffff0000, v0
	s_waitcnt vmcnt(6)
	v_lshl_add_u32 v0, v4, 12, v0
	v_and_b32_e32 v1, 1, v3
	v_lshl_or_b32 v0, v1, 6, v0
	v_readlane_b32 s12, v254, 17
	v_bitop3_b32 v143, s11, v16, v17 bitop3:0xf6
	s_cselect_b64 s[10:11], -1, 0
	v_or_b32_e32 v144, s14, v14
	v_mov_b32_e32 v135, v169
	v_lshl_add_u32 v136, v5, 1, v0
	v_mov_b32_e32 v137, v169
	s_mov_b32 s48, 0
	v_add_u32_e32 v145, 0, v15
	v_readlane_b32 s49, v254, 14
	s_mov_b32 s52, s12
	s_barrier
	v_readlane_b32 s13, v254, 18
	s_branch .LBB0_158

; #define PG8_STAGE(bufoff, gbase, voff) do { _Pragma("unroll") for (int _i = 0; _i < 2; ++_i) \
;         __builtin_amdgcn_global_load_lds((const unsigned*)((const char*)(gbase) + (voff)[_i]), (LAS unsigned*)(lds + (bufoff) + ldsw + _i * 8192), 16, 0, 0); } while (0)
; #define PG8_WAIT_V(n) asm volatile("s_waitcnt vmcnt(" #n ")" ::: "memory")
; #define PG8_BAR __builtin_amdgcn_s_barrier()
; template <class Epi>
; __device__ __forceinline__ void gemm_phase(LAS unsigned char* lds, const Gemm g, const StaticOrder& S, const Epi& E, const int tid) {
;     ...
;     const char* cA = PG8_APTR(cur); const char* cB = PG8_BPTR(cur);
;     PG8_STAGE(PG8_SB(0, 0), cB, voffB); PG8_STAGE(PG8_SB(0, 1), cB + hsB, voffB); PG8_STAGE(PG8_SA(0, 0), cA, voffA); PG8_STAGE(PG8_SA(0, 1), cA + hsA, voffA);
;     if (wr == 1) PG8_BAR;
;     PG8_WAIT_V(2); PG8_BAR;
;     PG8_STAGE(PG8_SB(1, 0), cB + kstep, voffB); PG8_STAGE(PG8_SA(1, 0), cA + kstep, voffA); PG8_STAGE(PG8_SB(1, 1), cB + hsB + kstep, voffB);
;     PG8_WAIT_V(6); PG8_BAR;
;     __device__ __forceinline__ void operator()(f32x4 (&acc)[2][2][4][2], const Unit& u, int wr, int wc, int fr, int fq) const {
;     ...
;             const int lane = fr + 16 * fq, rr = lane >> 2, cg = lane & 3;
;             const int pullx = (4 * fr + fq) * 4, pullr = (rr + 16 * cg) * 4;
;             _Float16* xc = xh + (size_t)(row_off + u.pm * BM + wr * 64 + rr) * D + u.pn * BM + wc * 32 + 8 * cg;
.LBB0_219:
	s_and_b64 s[8:9], s[4:5], exec
	v_readlane_b32 s8, v252, 19
	v_readlane_b32 s9, v252, 20
	v_readlane_b32 s11, v252, 22
	s_cselect_b32 s9, s9, 0
	s_cselect_b32 s8, s8, 0
	s_add_u32 s49, s55, 0x4000
	v_readlane_b32 s34, v254, 25
	v_readlane_b32 s16, v252, 27
	s_addc_u32 s52, s60, 0
	v_bfe_u32 v16, v214, 4, 2
	s_lshl_b32 s11, s24, 5
	v_mov_b32_e32 v147, v169
	v_readlane_b32 s35, v254, 26
	v_readlane_b32 s12, v252, 23
	v_and_b32_e32 v192, 15, v214
	v_lshlrev_b32_e32 v17, 4, v16
	v_lshlrev_b32_e32 v18, 2, v214
	s_and_b32 s16, s11, 0x60
	s_add_i32 m0, s44, 0x18000
	v_lshl_add_u64 v[0:1], v[0:1], 0, s[28:29]
	v_lshl_add_u64 v[12:13], s[34:35], 0, v[146:147]
	v_mov_b32_e32 v143, v169
	s_lshl_b32 s53, s25, 6
	v_lshl_or_b32 v17, v192, 6, v17
	s_lshl_b32 s12, s25, 13
	v_and_b32_e32 v18, 32, v18
	s_lshl_b32 s11, s16, 7
	global_load_lds_dwordx4 v[0:1], off
	v_lshl_add_u64 v[0:1], v[2:3], 0, s[28:29]
	s_add_i32 m0, s44, 0x1a000
	s_add_i32 s56, s44, 0x8000
	s_add_i32 s57, s44, 0xa000
	v_lshl_add_u64 v[14:15], s[34:35], 0, v[142:143]
	v_readlane_b32 s13, v252, 24
	v_bitop3_b32 v19, v17, s12, v18 bitop3:0xde
	global_load_lds_dwordx4 v[0:1], off
	v_lshl_add_u64 v[0:1], v[12:13], 0, s[28:29]
	s_mov_b32 m0, s56
	s_add_u32 s12, s0, 0x160080
	global_load_lds_dwordx4 v[0:1], off
	v_lshl_add_u64 v[0:1], v[14:15], 0, s[28:29]
	s_mov_b32 m0, s57
	s_addc_u32 s13, s1, 0
	global_load_lds_dwordx4 v[0:1], off
	s_add_i32 m0, s44, 0x1c000
	v_lshl_add_u64 v[0:1], s[12:13], 0, v[144:145]
	global_load_lds_dwordx4 v[0:1], off
	v_lshl_add_u64 v[0:1], s[12:13], 0, v[140:141]
	s_add_i32 m0, s44, 0x1e000
	v_readlane_b32 s17, v252, 28
	global_load_lds_dwordx4 v[0:1], off
	s_waitcnt vmcnt(8)
	s_barrier
	v_lshlrev_b32_e32 v1, 4, v192
	s_cmpk_lt_u32 s2, 0x100
	v_and_b32_e32 v0, 3, v214
	v_lshl_or_b32 v196, v16, 2, v1
	v_and_b32_e32 v1, 60, v214
	s_movk_i32 s2, 0x1600
	v_readlane_b32 s14, v252, 25
	v_readlane_b32 s15, v252, 26
	v_lshl_or_b32 v197, v0, 6, v1
	v_lshrrev_b32_e32 v1, 1, v9
	v_mul_lo_u32 v2, v8, s2
	s_mov_b32 s17, 0x16000
	v_mad_u64_u32 v[2:3], s[14:15], v1, s17, v[2:3]
	v_or_b32_e32 v1, v2, v10
	v_add_lshl_u32 v168, v1, v11, 1
	v_lshrrev_b32_e32 v1, 1, v4
	v_mul_lo_u32 v2, v5, s2
	v_readlane_b32 s18, v252, 29
	v_readlane_b32 s19, v252, 30
	v_mad_u64_u32 v[2:3], s[14:15], v1, s17, v[2:3]
	v_readlane_b32 s10, v252, 21
	v_readlane_b32 s20, v252, 31
	v_readlane_b32 s21, v252, 32
	s_waitcnt vmcnt(6)
	s_mov_b64 s[18:19], 0x160080
	v_or_b32_e32 v1, v2, v6
	v_bitop3_b32 v193, s11, v17, v18 bitop3:0xf6
	s_cselect_b64 s[10:11], -1, 0
	v_lshlrev_b32_e32 v0, 3, v0
	s_cmp_lg_u64 s[8:9], 0
	v_lshl_add_u64 v[148:149], v[168:169], 0, s[18:19]
	v_add_lshl_u32 v168, v1, v7, 1
	v_readlane_b32 s14, v254, 42
	v_readlane_b32 s20, v255, 2
	s_mov_b32 s48, 0
	v_lshl_or_b32 v194, v16, 3, s16
	v_bfe_u32 v195, v214, 2, 4
	s_cselect_b64 s[12:13], -1, 0
	v_lshl_add_u64 v[150:151], v[168:169], 0, s[18:19]
	v_add_u32_e32 v198, 0, v19
	s_lshl_b32 s60, s16, 1
	v_lshlrev_b32_e32 v168, 1, v0
	v_readlane_b32 s67, v254, 53
	s_mov_b32 s68, s14
	s_mov_b64 s[18:19], s[34:35]
	v_readlane_b32 s21, v255, 3
	v_readlane_b32 s22, v252, 33
	v_readlane_b32 s23, v252, 34
	s_barrier
	v_readlane_b32 s15, v254, 43
	s_branch .LBB0_222

; #define PG8_STAGE(bufoff, gbase, voff) do { _Pragma("unroll") for (int _i = 0; _i < 2; ++_i) \
;         __builtin_amdgcn_global_load_lds((const unsigned*)((const char*)(gbase) + (voff)[_i]), (LAS unsigned*)(lds + (bufoff) + ldsw + _i * 8192), 16, 0, 0); } while (0)
; #define PG8_WAIT_V(n) asm volatile("s_waitcnt vmcnt(" #n ")" ::: "memory")
; #define PG8_BAR __builtin_amdgcn_s_barrier()
; template <class Epi>
; __device__ __forceinline__ void gemm_phase(LAS unsigned char* lds, const Gemm g, const StaticOrder& S, const Epi& E, const int tid) {
;     ...
;     for (int i = 0; i < 2; ++i) { int R, C; stage_rc(tid * 16 + i * 8192, R, C); const int Rb = Epi::PERM ? ((R & ~31) + perm32(R & 31)) : R;
;         voffA[i] = (unsigned)(R * g.lda + C) * 2u; voffB[i] = (unsigned)(Rb * g.ldb + C) * 2u; }
;     const size_t kstep = (size_t)(BK * 2);
;     const size_t hsA = (size_t)HALF * g.lda * 2, hsB = (size_t)HALF * g.ldb * 2;
;     const size_t tsA = 2 * hsA, tsB = 2 * hsB;
;     const unsigned ldsw = (unsigned)wid * 1024u;
;     const int aoff = lds_byte(wr * 64 + fr, fq * 8), boff = lds_byte(wc * 32 + fr, fq * 8);
;     ...
;     const char* cA = PG8_APTR(cur); const char* cB = PG8_BPTR(cur);
;     PG8_STAGE(PG8_SB(0, 0), cB, voffB); PG8_STAGE(PG8_SB(0, 1), cB + hsB, voffB); PG8_STAGE(PG8_SA(0, 0), cA, voffA); PG8_STAGE(PG8_SA(0, 1), cA + hsA, voffA);
;     if (wr == 1) PG8_BAR;
;     PG8_WAIT_V(2); PG8_BAR;
;     PG8_STAGE(PG8_SB(1, 0), cB + kstep, voffB); PG8_STAGE(PG8_SA(1, 0), cA + kstep, voffA); PG8_STAGE(PG8_SB(1, 1), cB + hsB + kstep, voffB);
;     PG8_WAIT_V(6); PG8_BAR;
.LBB0_348:
	v_readlane_b32 s42, v255, 36
	v_mov_b32_e32 v133, v169
	v_readlane_b32 s43, v255, 37
	v_mov_b32_e32 v129, v169
	v_mov_b32_e32 v135, v169
	v_lshl_add_u64 v[6:7], s[42:43], 0, v[132:133]
	v_lshl_add_u64 v[8:9], s[42:43], 0, v[128:129]
	s_add_i32 m0, s58, 0x18000
	v_lshl_add_u64 v[6:7], v[6:7], 0, s[28:29]
	v_lshl_add_u64 v[10:11], s[0:1], 0, v[134:135]
	v_mov_b32_e32 v131, v169
	global_load_lds_dwordx4 v[6:7], off
	v_lshl_add_u64 v[6:7], v[8:9], 0, s[28:29]
	s_add_i32 m0, s58, 0x1a000
	s_add_i32 s6, s58, 0x8000
	v_lshl_add_u64 v[12:13], s[0:1], 0, v[130:131]
	global_load_lds_dwordx4 v[6:7], off
	v_lshl_add_u64 v[6:7], v[10:11], 0, s[28:29]
	s_mov_b32 m0, s6
	s_add_i32 s7, s58, 0xa000
	v_readlane_b32 s16, v255, 38
	global_load_lds_dwordx4 v[6:7], off
	v_lshl_add_u64 v[6:7], v[12:13], 0, s[28:29]
	s_mov_b32 m0, s7
	v_readlane_b32 s17, v255, 39
	global_load_lds_dwordx4 v[6:7], off
	s_add_i32 m0, s58, 0x1c000
	v_lshl_add_u64 v[6:7], s[16:17], 0, v[132:133]
	global_load_lds_dwordx4 v[6:7], off
	v_lshl_add_u64 v[6:7], s[16:17], 0, v[128:129]
	s_add_i32 m0, s58, 0x1e000
	s_and_b32 s12, s12, 3
	global_load_lds_dwordx4 v[6:7], off
	s_waitcnt vmcnt(8)
	s_barrier
	v_lshrrev_b32_e32 v6, 1, v214
	v_and_b32_e32 v6, 24, v6
	v_and_b32_e32 v7, 15, v214
	v_lshlrev_b32_e32 v8, 1, v6
	v_lshl_or_b32 v162, s11, 6, v7
	v_lshl_or_b32 v7, v7, 6, v8
	v_lshlrev_b32_e32 v8, 2, v214
	s_lshl_b32 s11, s11, 13
	v_and_b32_e32 v8, 32, v8
	v_bitop3_b32 v9, v7, s11, v8 bitop3:0xde
	s_lshl_b32 s11, s12, 12
	v_bitop3_b32 v163, s11, v7, v8 bitop3:0xf6
	v_lshlrev_b32_e32 v7, 15, v4
	v_and_b32_e32 v7, 0xffff0000, v7
	v_lshl_add_u32 v3, v3, 12, v7
	v_and_b32_e32 v4, 1, v4
	v_lshl_or_b32 v3, v4, 6, v3
	v_lshl_add_u32 v138, v5, 1, v3
	v_lshlrev_b32_e32 v3, 15, v0
	s_cmpk_lt_u32 s10, 0x100
	v_and_b32_e32 v3, 0xffff0000, v3
	s_waitcnt vmcnt(6)
	s_cselect_b64 s[34:35], -1, 0
	v_lshl_or_b32 v164, s12, 5, v6
	s_lshl_b32 s10, s12, 6
	v_readlane_b32 s12, v255, 14
	v_lshl_add_u32 v1, v1, 12, v3
	v_and_b32_e32 v0, 1, v0
	v_lshlrev_b32_e32 v168, 2, v6
	v_readlane_b32 s13, v255, 15
	v_lshl_or_b32 v0, v0, 6, v1
	s_lshl_b32 s44, s10, 1
	v_readlane_b32 s10, v254, 57
	v_lshl_add_u64 v[136:137], s[12:13], 0, v[168:169]
	v_mov_b32_e32 v139, v169
	v_lshl_add_u32 v140, v2, 1, v0
	v_mov_b32_e32 v141, v169
	s_mov_b32 s68, 0
	v_add_u32_e32 v165, 0, v9
	v_lshlrev_b32_e32 v142, 1, v6
	v_readlane_b32 s45, v254, 32
	s_mov_b32 s60, s10
	s_barrier
	v_readlane_b32 s11, v254, 58
	s_branch .LBB0_351

; #define PG8_STAGE(bufoff, gbase, voff) do { _Pragma("unroll") for (int _i = 0; _i < 2; ++_i) \
;         __builtin_amdgcn_global_load_lds((const unsigned*)((const char*)(gbase) + (voff)[_i]), (LAS unsigned*)(lds + (bufoff) + ldsw + _i * 8192), 16, 0, 0); } while (0)
; #define PG8_WAIT_V(n) asm volatile("s_waitcnt vmcnt(" #n ")" ::: "memory")
; #define PG8_BAR __builtin_amdgcn_s_barrier()
; template <class Epi>
; __device__ __forceinline__ void gemm_phase(LAS unsigned char* lds, const Gemm g, const StaticOrder& S, const Epi& E, const int tid) {
;     ...
;     f32x4 acc[2][2][4][2];
; #pragma unroll
;     for (int a = 0; a < 2; ++a)
; #pragma unroll
;         for (int b = 0; b < 2; ++b)
; #pragma unroll
;             for (int m = 0; m < 4; ++m)
; #pragma unroll
;                 for (int n = 0; n < 2; ++n) acc[a][b][m][n] = (f32x4){0.f, 0.f, 0.f, 0.f};
;     ...
;     const char* cA = PG8_APTR(cur); const char* cB = PG8_BPTR(cur);
;     PG8_STAGE(PG8_SB(0, 0), cB, voffB); PG8_STAGE(PG8_SB(0, 1), cB + hsB, voffB); PG8_STAGE(PG8_SA(0, 0), cA, voffA); PG8_STAGE(PG8_SA(0, 1), cA + hsA, voffA);
;     if (wr == 1) PG8_BAR;
;     PG8_WAIT_V(2); PG8_BAR;
;     PG8_STAGE(PG8_SB(1, 0), cB + kstep, voffB); PG8_STAGE(PG8_SA(1, 0), cA + kstep, voffA); PG8_STAGE(PG8_SB(1, 1), cB + hsB + kstep, voffB);
;     PG8_WAIT_V(6); PG8_BAR;
.LBB0_811:
	v_lshrrev_b32_e32 v17, 1, v214
	v_readlane_b32 s48, v255, 28
	v_and_b32_e32 v17, 24, v17
	v_readlane_b32 s49, v255, 29
	v_and_b32_e32 v16, 15, v214
	v_lshlrev_b32_e32 v18, 1, v17
	v_lshl_add_u64 v[8:9], s[48:49], 0, v[168:169]
	v_mov_b32_e32 v129, v169
	v_readlane_b32 s36, v254, 36
	v_lshl_or_b32 v231, s12, 6, v16
	v_lshl_or_b32 v16, v16, 6, v18
	v_lshlrev_b32_e32 v18, 2, v214
	s_lshl_b32 s1, s1, 5
	v_lshl_add_u64 v[10:11], s[48:49], 0, v[128:129]
	v_mov_b32_e32 v133, v169
	v_readlane_b32 s37, v254, 37
	s_lshl_b32 s12, s12, 13
	v_and_b32_e32 v18, 32, v18
	s_and_b32 s1, s1, 0x60
	s_add_i32 m0, s7, 0x18000
	v_lshl_add_u64 v[8:9], v[8:9], 0, s[28:29]
	v_lshl_add_u64 v[12:13], s[36:37], 0, v[132:133]
	v_mov_b32_e32 v131, v169
	v_bitop3_b32 v19, v16, s12, v18 bitop3:0xde
	s_lshl_b32 s12, s1, 7
	global_load_lds_dwordx4 v[8:9], off
	v_lshl_add_u64 v[8:9], v[10:11], 0, s[28:29]
	s_add_i32 m0, s7, 0x1a000
	s_add_i32 s56, s7, 0x8000
	v_lshl_add_u64 v[14:15], s[36:37], 0, v[130:131]
	v_bitop3_b32 v232, s12, v16, v18 bitop3:0xf6
	global_load_lds_dwordx4 v[8:9], off
	v_lshl_add_u64 v[8:9], v[12:13], 0, s[28:29]
	s_mov_b32 m0, s56
	s_add_i32 s57, s7, 0xa000
	v_readlane_b32 s12, v255, 30
	global_load_lds_dwordx4 v[8:9], off
	v_lshl_add_u64 v[8:9], v[14:15], 0, s[28:29]
	s_mov_b32 m0, s57
	v_readlane_b32 s13, v255, 31
	global_load_lds_dwordx4 v[8:9], off
	s_add_i32 m0, s7, 0x1c000
	v_lshl_add_u64 v[8:9], s[12:13], 0, v[168:169]
	global_load_lds_dwordx4 v[8:9], off
	v_lshl_add_u64 v[8:9], s[12:13], 0, v[128:129]
	s_add_i32 m0, s7, 0x1e000
	s_movk_i32 s15, 0xc00
	global_load_lds_dwordx4 v[8:9], off
	s_waitcnt vmcnt(8)
	s_barrier
	v_lshrrev_b32_e32 v5, 1, v5
	v_mul_lo_u32 v4, v4, s15
	s_mov_b32 s14, 0xc000
	s_cmpk_lt_u32 s0, 0x100
	v_or_b32_e32 v233, s1, v17
	v_mad_u64_u32 v[4:5], s[0:1], v5, s14, v[4:5]
	v_or_b32_e32 v4, v4, v6
	v_add_lshl_u32 v4, v4, v7, 1
	v_mov_b32_e32 v5, v169
	s_mov_b64 s[18:19], 0xc0080
	v_lshl_add_u64 v[134:135], v[4:5], 0, s[18:19]
	v_lshrrev_b32_e32 v4, 1, v0
	v_mul_lo_u32 v0, v1, s15
	v_mad_u64_u32 v[0:1], s[0:1], v4, s14, v[0:1]
	v_or_b32_e32 v0, v0, v2
	s_waitcnt vmcnt(6)
	v_add_lshl_u32 v0, v0, v3, 1
	v_mov_b32_e32 v1, v169
	v_lshl_add_u64 v[136:137], v[0:1], 0, s[18:19]
	s_cselect_b64 s[12:13], -1, 0
	s_mov_b64 s[16:17], 0xc0080
	s_mov_b32 s52, 0
	v_add_u32_e32 v234, 0, v19
	v_readlane_b32 s53, v254, 29
	v_readlane_b32 s60, v254, 33
	s_mov_b32 s58, 0
	v_mov_b64_e32 v[0:1], 0
	v_mov_b64_e32 v[2:3], 0
	v_mov_b64_e32 v[4:5], 0
	v_mov_b64_e32 v[6:7], 0
	v_mov_b64_e32 v[8:9], 0
	v_mov_b64_e32 v[10:11], 0
	v_mov_b64_e32 v[12:13], 0
	v_mov_b64_e32 v[14:15], 0
	v_mov_b64_e32 v[16:17], 0
	v_mov_b64_e32 v[18:19], 0
	v_mov_b64_e32 v[20:21], 0
	v_mov_b64_e32 v[22:23], 0
	v_mov_b64_e32 v[24:25], 0
	v_mov_b64_e32 v[26:27], 0
	v_mov_b64_e32 v[28:29], 0
	v_mov_b64_e32 v[30:31], 0
	v_mov_b64_e32 v[32:33], 0
	v_mov_b64_e32 v[34:35], 0
	v_mov_b64_e32 v[36:37], 0
	v_mov_b64_e32 v[38:39], 0
	v_mov_b64_e32 v[40:41], 0
	v_mov_b64_e32 v[42:43], 0
	v_mov_b64_e32 v[44:45], 0
	v_mov_b64_e32 v[46:47], 0
	v_mov_b64_e32 v[48:49], 0
	v_mov_b64_e32 v[50:51], 0
	v_mov_b64_e32 v[52:53], 0
	v_mov_b64_e32 v[54:55], 0
	v_mov_b64_e32 v[56:57], 0
	v_mov_b64_e32 v[58:59], 0
	v_mov_b64_e32 v[60:61], 0
	v_mov_b64_e32 v[62:63], 0
	v_mov_b64_e32 v[64:65], 0
	v_mov_b64_e32 v[66:67], 0
	v_mov_b64_e32 v[68:69], 0
	v_mov_b64_e32 v[70:71], 0
	v_mov_b64_e32 v[72:73], 0
	v_mov_b64_e32 v[74:75], 0
	v_mov_b64_e32 v[76:77], 0
	v_mov_b64_e32 v[78:79], 0
	v_mov_b64_e32 v[80:81], 0
	v_mov_b64_e32 v[82:83], 0
	v_mov_b64_e32 v[84:85], 0
	v_mov_b64_e32 v[86:87], 0
	v_mov_b64_e32 v[88:89], 0
	v_mov_b64_e32 v[90:91], 0
	v_mov_b64_e32 v[92:93], 0
	v_mov_b64_e32 v[94:95], 0
	v_mov_b64_e32 v[96:97], 0
	v_mov_b64_e32 v[98:99], 0
	v_mov_b64_e32 v[100:101], 0
	v_mov_b64_e32 v[102:103], 0
	v_mov_b64_e32 v[104:105], 0
	v_mov_b64_e32 v[106:107], 0
	v_mov_b64_e32 v[108:109], 0
	v_mov_b64_e32 v[110:111], 0
	v_mov_b64_e32 v[112:113], 0
	v_mov_b64_e32 v[114:115], 0
	v_mov_b64_e32 v[116:117], 0
	v_mov_b64_e32 v[118:119], 0
	v_mov_b64_e32 v[120:121], 0
	v_mov_b64_e32 v[122:123], 0
	v_mov_b64_e32 v[124:125], 0
	v_mov_b64_e32 v[126:127], 0
	s_barrier
	s_branch .LBB0_814

; #define PG8_STAGE(bufoff, gbase, voff) do { _Pragma("unroll") for (int _i = 0; _i < 2; ++_i) \
;         __builtin_amdgcn_global_load_lds((const unsigned*)((const char*)(gbase) + (voff)[_i]), (LAS unsigned*)(lds + (bufoff) + ldsw + _i * 8192), 16, 0, 0); } while (0)
; #define PG8_WAIT_V(n) asm volatile("s_waitcnt vmcnt(" #n ")" ::: "memory")
; #define PG8_BAR __builtin_amdgcn_s_barrier()
; template <class Epi>
; __device__ __forceinline__ void gemm_phase(LAS unsigned char* lds, const Gemm g, const StaticOrder& S, const Epi& E, const int tid) {
;     ...
;     const char* cA = PG8_APTR(cur); const char* cB = PG8_BPTR(cur);
;     PG8_STAGE(PG8_SB(0, 0), cB, voffB); PG8_STAGE(PG8_SB(0, 1), cB + hsB, voffB); PG8_STAGE(PG8_SA(0, 0), cA, voffA); PG8_STAGE(PG8_SA(0, 1), cA + hsA, voffA);
;     if (wr == 1) PG8_BAR;
;     PG8_WAIT_V(2); PG8_BAR;
;     PG8_STAGE(PG8_SB(1, 0), cB + kstep, voffB); PG8_STAGE(PG8_SA(1, 0), cA + kstep, voffA); PG8_STAGE(PG8_SB(1, 1), cB + hsB + kstep, voffB);
;     PG8_WAIT_V(6); PG8_BAR;
;     __device__ __forceinline__ void operator()(f32x4 (&acc)[2][2][4][2], const Unit& u, int wr, int wc, int fr, int fq) const {
;     ...
;             const int lane = fr + 16 * fq, rr = lane >> 2, cg = lane & 3;
;             const int pullx = (4 * fr + fq) * 4, pullr = (rr + 16 * cg) * 4;
;             _Float16* xc = xh + (size_t)(row_off + u.pm * BM + wr * 64 + rr) * D + u.pn * BM + wc * 32 + 8 * cg;
.LBB0_883:
	v_bfe_u32 v14, v214, 4, 2
	s_add_u32 s42, s20, 0xa000
	v_and_b32_e32 v15, 15, v214
	v_lshlrev_b32_e32 v16, 4, v14
	v_lshlrev_b32_e32 v17, 2, v214
	s_addc_u32 s43, s21, 0
	v_lshl_or_b32 v16, v15, 6, v16
	s_lshl_b32 s2, s8, 13
	v_and_b32_e32 v17, 32, v17
	v_readlane_b32 s16, v254, 46
	v_bitop3_b32 v18, v16, s2, v17 bitop3:0xde
	s_lshl_b32 s2, s7, 5
	v_mov_b32_e32 v191, v169
	v_readlane_b32 s17, v254, 47
	s_and_b32 s2, s2, 0x60
	s_add_i32 m0, s36, 0x18000
	v_lshl_add_u64 v[0:1], v[0:1], 0, s[28:29]
	v_lshl_add_u64 v[10:11], s[16:17], 0, v[190:191]
	v_mov_b32_e32 v187, v169
	s_lshl_b32 s7, s2, 7
	global_load_lds_dwordx4 v[0:1], off
	v_lshl_add_u64 v[0:1], v[2:3], 0, s[28:29]
	s_add_i32 m0, s36, 0x1a000
	s_add_i32 s44, s36, 0x8000
	s_add_i32 s45, s36, 0xa000
	v_lshl_add_u64 v[12:13], s[16:17], 0, v[186:187]
	global_load_lds_dwordx4 v[0:1], off
	v_lshl_add_u64 v[0:1], v[10:11], 0, s[28:29]
	s_mov_b32 m0, s44
	s_add_u32 s10, s0, 0x80080
	global_load_lds_dwordx4 v[0:1], off
	v_lshl_add_u64 v[0:1], v[12:13], 0, s[28:29]
	s_mov_b32 m0, s45
	s_addc_u32 s11, s1, 0
	global_load_lds_dwordx4 v[0:1], off
	s_add_i32 m0, s36, 0x1c000
	v_lshl_add_u64 v[0:1], s[10:11], 0, v[188:189]
	global_load_lds_dwordx4 v[0:1], off
	v_lshl_add_u64 v[0:1], s[10:11], 0, v[184:185]
	s_add_i32 m0, s36, 0x1e000
	v_lshlrev_b32_e32 v2, 4, v15
	global_load_lds_dwordx4 v[0:1], off
	s_waitcnt vmcnt(8)
	s_barrier
	v_bfe_u32 v1, v214, 2, 4
	v_lshl_or_b32 v208, s8, 6, v1
	v_lshlrev_b32_e32 v1, 15, v8
	v_and_b32_e32 v0, 3, v214
	v_lshl_or_b32 v206, v14, 2, v2
	v_and_b32_e32 v2, 60, v214
	v_and_b32_e32 v1, 0xffff0000, v1
	v_lshl_or_b32 v207, v0, 6, v2
	v_lshl_add_u32 v1, v7, 12, v1
	v_and_b32_e32 v2, 1, v8
	v_lshl_or_b32 v1, v2, 6, v1
	v_lshl_add_u32 v192, v9, 1, v1
	v_lshlrev_b32_e32 v1, 15, v4
	v_and_b32_e32 v1, 0xffff0000, v1
	s_waitcnt vmcnt(6)
	v_lshl_add_u32 v1, v5, 12, v1
	v_and_b32_e32 v2, 1, v4
	s_cmpk_lt_u32 s6, 0x100
	v_lshlrev_b32_e32 v0, 3, v0
	v_lshl_or_b32 v1, v2, 6, v1
	v_readlane_b32 s8, v254, 42
	v_bitop3_b32 v204, s7, v16, v17 bitop3:0xf6
	v_lshl_or_b32 v205, v14, 3, s2
	s_cselect_b64 s[6:7], -1, 0
	v_mov_b32_e32 v193, v169
	v_lshl_add_u32 v194, v6, 1, v1
	v_mov_b32_e32 v195, v169
	s_mov_b32 s46, 0
	v_add_u32_e32 v209, 0, v18
	s_lshl_b32 s60, s2, 1
	v_lshlrev_b32_e32 v168, 1, v0
	v_readlane_b32 s48, v254, 53
	s_mov_b32 s47, s8
	s_barrier
	v_readlane_b32 s9, v254, 43
	s_branch .LBB0_886

; #define PG8_STAGE(bufoff, gbase, voff) do { _Pragma("unroll") for (int _i = 0; _i < 2; ++_i) \
;         __builtin_amdgcn_global_load_lds((const unsigned*)((const char*)(gbase) + (voff)[_i]), (LAS unsigned*)(lds + (bufoff) + ldsw + _i * 8192), 16, 0, 0); } while (0)
; #define PG8_WAIT_V(n) asm volatile("s_waitcnt vmcnt(" #n ")" ::: "memory")
; #define PG8_BAR __builtin_amdgcn_s_barrier()
; template <class Epi>
; __device__ __forceinline__ void gemm_phase(LAS unsigned char* lds, const Gemm g, const StaticOrder& S, const Epi& E, const int tid) {
;     ...
;     for (int i = 0; i < 2; ++i) { int R, C; stage_rc(tid * 16 + i * 8192, R, C); const int Rb = Epi::PERM ? ((R & ~31) + perm32(R & 31)) : R;
;         voffA[i] = (unsigned)(R * g.lda + C) * 2u; voffB[i] = (unsigned)(Rb * g.ldb + C) * 2u; }
;     const size_t kstep = (size_t)(BK * 2);
;     const size_t hsA = (size_t)HALF * g.lda * 2, hsB = (size_t)HALF * g.ldb * 2;
;     const size_t tsA = 2 * hsA, tsB = 2 * hsB;
;     const unsigned ldsw = (unsigned)wid * 1024u;
;     const int aoff = lds_byte(wr * 64 + fr, fq * 8), boff = lds_byte(wc * 32 + fr, fq * 8);
;     ...
;     const char* cA = PG8_APTR(cur); const char* cB = PG8_BPTR(cur);
;     PG8_STAGE(PG8_SB(0, 0), cB, voffB); PG8_STAGE(PG8_SB(0, 1), cB + hsB, voffB); PG8_STAGE(PG8_SA(0, 0), cA, voffA); PG8_STAGE(PG8_SA(0, 1), cA + hsA, voffA);
;     if (wr == 1) PG8_BAR;
;     PG8_WAIT_V(2); PG8_BAR;
;     PG8_STAGE(PG8_SB(1, 0), cB + kstep, voffB); PG8_STAGE(PG8_SA(1, 0), cA + kstep, voffA); PG8_STAGE(PG8_SB(1, 1), cB + hsB + kstep, voffB);
;     PG8_WAIT_V(6); PG8_BAR;
.LBB0_998:
	v_lshrrev_b32_e32 v14, 1, v214
	v_and_b32_e32 v15, 15, v214
	v_and_b32_e32 v14, 24, v14
	v_lshlrev_b32_e32 v16, 6, v15
	v_lshlrev_b32_e32 v17, 2, v214
	v_lshl_or_b32 v16, v14, 1, v16
	v_and_b32_e32 v17, 32, v17
	s_lshl_b32 s2, s10, 13
	v_mov_b32_e32 v133, v169
	v_lshl_add_u64 v[6:7], s[0:1], 0, v[168:169]
	v_readlane_b32 s18, v254, 19
	v_lshl_or_b32 v142, s10, 6, v15
	v_bitop3_b32 v15, v16, s2, v17 bitop3:0xde
	s_lshl_b32 s2, s9, 5
	v_mov_b32_e32 v129, v169
	v_lshl_add_u64 v[8:9], s[0:1], 0, v[132:133]
	v_readlane_b32 s19, v254, 20
	s_and_b32 s2, s2, 0x60
	s_add_i32 m0, s40, 0x18000
	v_lshl_add_u64 v[6:7], v[6:7], 0, s[28:29]
	v_mov_b32_e32 v131, v169
	v_lshl_add_u64 v[10:11], s[18:19], 0, v[128:129]
	s_lshl_b32 s9, s2, 7
	global_load_lds_dwordx4 v[6:7], off
	v_lshl_add_u64 v[6:7], v[8:9], 0, s[28:29]
	s_add_i32 m0, s40, 0x1a000
	s_add_i32 s44, s40, 0x8000
	s_add_i32 s45, s40, 0xa000
	v_lshl_add_u64 v[12:13], s[18:19], 0, v[130:131]
	global_load_lds_dwordx4 v[6:7], off
	v_lshl_add_u64 v[6:7], v[10:11], 0, s[28:29]
	s_mov_b32 m0, s44
	s_add_u32 s10, s0, 0x80080
	global_load_lds_dwordx4 v[6:7], off
	v_lshl_add_u64 v[6:7], v[12:13], 0, s[28:29]
	s_mov_b32 m0, s45
	s_addc_u32 s11, s1, 0
	global_load_lds_dwordx4 v[6:7], off
	s_add_i32 m0, s40, 0x1c000
	v_lshl_add_u64 v[6:7], s[10:11], 0, v[168:169]
	global_load_lds_dwordx4 v[6:7], off
	v_lshl_add_u64 v[6:7], s[10:11], 0, v[132:133]
	s_add_i32 m0, s40, 0x1e000
	s_cmpk_lt_u32 s8, 0x100
	global_load_lds_dwordx4 v[6:7], off
	s_waitcnt vmcnt(8)
	s_barrier
	v_lshlrev_b32_e32 v6, 15, v0
	v_and_b32_e32 v6, 0xffff0000, v6
	v_lshl_add_u32 v1, v1, 12, v6
	v_and_b32_e32 v0, 1, v0
	v_lshl_or_b32 v0, v0, 6, v1
	v_lshl_add_u32 v134, v2, 1, v0
	v_lshlrev_b32_e32 v0, 15, v3
	v_and_b32_e32 v0, 0xffff0000, v0
	s_waitcnt vmcnt(6)
	v_lshl_add_u32 v0, v4, 12, v0
	v_and_b32_e32 v1, 1, v3
	v_lshl_or_b32 v0, v1, 6, v0
	v_readlane_b32 s10, v254, 17
	v_bitop3_b32 v143, s9, v16, v17 bitop3:0xf6
	s_cselect_b64 s[8:9], -1, 0
	v_or_b32_e32 v144, s2, v14
	v_mov_b32_e32 v135, v169
	v_lshl_add_u32 v136, v5, 1, v0
	v_mov_b32_e32 v137, v169
	s_mov_b32 s46, 0
	v_add_u32_e32 v145, 0, v15
	v_readlane_b32 s47, v254, 14
	s_mov_b32 s48, s10
	s_barrier
	v_readlane_b32 s11, v254, 18
	s_branch .LBB0_1001

; #define PG8_STAGE(bufoff, gbase, voff) do { _Pragma("unroll") for (int _i = 0; _i < 2; ++_i) \
;         __builtin_amdgcn_global_load_lds((const unsigned*)((const char*)(gbase) + (voff)[_i]), (LAS unsigned*)(lds + (bufoff) + ldsw + _i * 8192), 16, 0, 0); } while (0)
; #define PG8_WAIT_V(n) asm volatile("s_waitcnt vmcnt(" #n ")" ::: "memory")
; #define PG8_BAR __builtin_amdgcn_s_barrier()
; template <class Epi>
; __device__ __forceinline__ void gemm_phase(LAS unsigned char* lds, const Gemm g, const StaticOrder& S, const Epi& E, const int tid) {
;     ...
;     const char* cA = PG8_APTR(cur); const char* cB = PG8_BPTR(cur);
;     PG8_STAGE(PG8_SB(0, 0), cB, voffB); PG8_STAGE(PG8_SB(0, 1), cB + hsB, voffB); PG8_STAGE(PG8_SA(0, 0), cA, voffA); PG8_STAGE(PG8_SA(0, 1), cA + hsA, voffA);
;     if (wr == 1) PG8_BAR;
;     PG8_WAIT_V(2); PG8_BAR;
;     PG8_STAGE(PG8_SB(1, 0), cB + kstep, voffB); PG8_STAGE(PG8_SA(1, 0), cA + kstep, voffA); PG8_STAGE(PG8_SB(1, 1), cB + hsB + kstep, voffB);
;     PG8_WAIT_V(6); PG8_BAR;
;     __device__ __forceinline__ void operator()(f32x4 (&acc)[2][2][4][2], const Unit& u, int wr, int wc, int fr, int fq) const {
;     ...
;             const int lane = fr + 16 * fq, rr = lane >> 2, cg = lane & 3;
;             const int pullx = (4 * fr + fq) * 4, pullr = (rr + 16 * cg) * 4;
;             _Float16* xc = xh + (size_t)(row_off + u.pm * BM + wr * 64 + rr) * D + u.pn * BM + wc * 32 + 8 * cg;
.LBB0_1062:
	v_bfe_u32 v16, v214, 4, 2
	s_add_u32 s42, s20, 0x10000
	v_and_b32_e32 v17, 15, v214
	v_lshlrev_b32_e32 v18, 4, v16
	v_lshlrev_b32_e32 v19, 2, v214
	s_addc_u32 s43, s21, 0
	v_lshl_or_b32 v18, v17, 6, v18
	s_lshl_b32 s2, s8, 13
	v_and_b32_e32 v19, 32, v19
	v_readlane_b32 s12, v254, 25
	v_bitop3_b32 v20, v18, s2, v19 bitop3:0xde
	s_lshl_b32 s2, s7, 5
	v_mov_b32_e32 v139, v169
	v_readlane_b32 s13, v254, 26
	s_and_b32 s2, s2, 0x60
	s_add_i32 m0, s34, 0x18000
	v_lshl_add_u64 v[0:1], v[0:1], 0, s[28:29]
	v_lshl_add_u64 v[12:13], s[12:13], 0, v[138:139]
	v_mov_b32_e32 v135, v169
	s_lshl_b32 s7, s2, 7
	global_load_lds_dwordx4 v[0:1], off
	v_lshl_add_u64 v[0:1], v[2:3], 0, s[28:29]
	s_add_i32 m0, s34, 0x1a000
	s_add_i32 s44, s34, 0x8000
	s_add_i32 s45, s34, 0xa000
	v_lshl_add_u64 v[14:15], s[12:13], 0, v[134:135]
	global_load_lds_dwordx4 v[0:1], off
	v_lshl_add_u64 v[0:1], v[12:13], 0, s[28:29]
	s_mov_b32 m0, s44
	s_add_u32 s10, s0, 0x160080
	global_load_lds_dwordx4 v[0:1], off
	v_lshl_add_u64 v[0:1], v[14:15], 0, s[28:29]
	s_mov_b32 m0, s45
	s_addc_u32 s11, s1, 0
	global_load_lds_dwordx4 v[0:1], off
	s_add_i32 m0, s34, 0x1c000
	v_lshl_add_u64 v[0:1], s[10:11], 0, v[136:137]
	global_load_lds_dwordx4 v[0:1], off
	v_lshl_add_u64 v[0:1], s[10:11], 0, v[132:133]
	s_add_i32 m0, s34, 0x1e000
	v_lshlrev_b32_e32 v2, 4, v17
	global_load_lds_dwordx4 v[0:1], off
	s_waitcnt vmcnt(8)
	s_barrier
	v_bfe_u32 v1, v214, 2, 4
	v_and_b32_e32 v0, 3, v214
	v_lshl_or_b32 v186, v16, 2, v2
	v_and_b32_e32 v2, 60, v214
	s_movk_i32 s10, 0x1600
	v_lshl_or_b32 v187, v0, 6, v2
	v_lshl_or_b32 v188, s8, 6, v1
	v_lshrrev_b32_e32 v1, 1, v9
	v_mul_lo_u32 v2, v8, s10
	s_mov_b32 s11, 0x16000
	v_mad_u64_u32 v[2:3], s[8:9], v1, s11, v[2:3]
	v_or_b32_e32 v1, v2, v10
	v_add_lshl_u32 v168, v1, v11, 1
	v_lshrrev_b32_e32 v1, 1, v4
	v_mul_lo_u32 v2, v5, s10
	v_mad_u64_u32 v[2:3], s[8:9], v1, s11, v[2:3]
	s_waitcnt vmcnt(6)
	s_mov_b64 s[14:15], 0x160080
	v_or_b32_e32 v1, v2, v6
	s_cmpk_lt_u32 s6, 0x100
	v_lshlrev_b32_e32 v0, 3, v0
	v_lshl_add_u64 v[140:141], v[168:169], 0, s[14:15]
	v_add_lshl_u32 v168, v1, v7, 1
	v_readlane_b32 s8, v254, 42
	v_bitop3_b32 v184, s7, v18, v19 bitop3:0xf6
	v_lshl_or_b32 v185, v16, 3, s2
	s_cselect_b64 s[6:7], -1, 0
	v_lshl_add_u64 v[142:143], v[168:169], 0, s[14:15]
	s_mov_b32 s46, 0
	v_add_u32_e32 v189, 0, v20
	s_lshl_b32 s60, s2, 1
	v_lshlrev_b32_e32 v168, 1, v0
	v_readlane_b32 s52, v254, 53
	s_mov_b32 s49, s8
	s_barrier
	v_readlane_b32 s9, v254, 43
	s_branch .LBB0_1065
